# overlap: 18 percent of the f32->bf16 weight prologue (layer-3 weights) moved into the idle tail of the sample-state streamer workgroups in the recurrence phases of layers 0-2 (same item code, called w
# speedup vs baseline: 1.0035x; 1.0035x over previous
; #define LAS __attribute__((address_space(3)))
; __global__ void __launch_bounds__(NTHR, 2) mega(const Args a) {
;     extern __shared__ __attribute__((aligned(16))) unsigned char lds_raw[];
;     LAS unsigned char* lds = (LAS unsigned char*)lds_raw;
;     const int wg0 = blockIdx.x, nwg0 = gridDim.x, tid = threadIdx.x;
;     for (int u = tid; u < (LDS_BYTES - LDSCTL_OFF) / 4; u += NTHR) ((LAS unsigned*)(lds + LDSCTL_OFF))[u] = 0u;
;     __syncthreads();
;     if (tid == 0) { const unsigned long long* src = (const unsigned long long*)&a.p;
; #pragma unroll
;         for (int i = 0; i < 25; ++i) *(LAS unsigned long long*)(lds + LDS_P_OFF + 8 * i) = src[i]; }
;     __syncthreads();
_Z4mega4Args:
	v_mov_b32_e32 v250, 0
	s_mov_b32 s3, 0x1b300
	v_writelane_b32 v250, s3, 2
	s_mov_b32 s3, 0x1b2ff
	v_writelane_b32 v250, s3, 3
	s_add_u32 s4, s0, 0xd0
	s_addc_u32 s5, s1, 0
	s_movk_i32 s3, 0x200
	v_writelane_b32 v249, s4, 0
	v_cmp_gt_u32_e32 vcc, s3, v0
	s_nop 0
	v_writelane_b32 v249, s5, 1
	s_and_saveexec_b64 s[6:7], vcc
	v_lshl_add_u32 v1, v0, 2, 0
	v_add_u32_e32 v1, 0x23800, v1
	v_mov_b32_e32 v2, 0
	ds_write_b32 v1, v2
	s_or_b64 exec, exec, s[6:7]
	s_waitcnt lgkmcnt(0)
	s_barrier
	v_cmp_eq_u32_e64 s[4:5], 0, v0
	s_mov_b64 s[22:23], exec
	s_nop 0
	v_writelane_b32 v249, s4, 2
	s_nop 1
	v_writelane_b32 v249, s5, 3
	s_and_b64 s[4:5], s[22:23], s[4:5]
	s_mov_b64 exec, s[4:5]
	s_cbranch_execz .LBB0_4
	s_load_dwordx16 s[4:19], s[0:1], 0x0
	s_add_i32 s20, 0, 0x23900
	s_load_dwordx16 s[48:63], s[0:1], 0x40
	v_mov_b32_e32 v1, s20
	s_add_i32 s20, 0, 0x23970
	s_waitcnt lgkmcnt(0)
	v_mov_b32_e32 v2, s4
	v_mov_b32_e32 v3, s5
	v_mov_b32_e32 v4, s6
	v_mov_b32_e32 v5, s7
	s_add_i32 s4, 0, 0x23910
	ds_write_b128 v1, v[2:5]
	v_mov_b32_e32 v2, s8
	v_mov_b32_e32 v3, s9
	v_mov_b32_e32 v4, s10
	v_mov_b32_e32 v5, s11
	v_mov_b32_e32 v1, s4
	s_add_i32 s4, 0, 0x23920
	ds_write_b128 v1, v[2:5]
	v_mov_b32_e32 v2, s12
	v_mov_b32_e32 v3, s13
	v_mov_b32_e32 v4, s14
	v_mov_b32_e32 v5, s15
	v_mov_b32_e32 v1, s4
	s_add_i32 s4, 0, 0x23930
	ds_write_b128 v1, v[2:5]
	v_mov_b32_e32 v2, s16
	v_mov_b32_e32 v3, s17
	v_mov_b32_e32 v4, s18
	v_mov_b32_e32 v5, s19
	v_mov_b32_e32 v1, s4
	s_add_i32 s4, 0, 0x23940
	ds_write_b128 v1, v[2:5]
	v_mov_b32_e32 v2, s48
	v_mov_b32_e32 v3, s49
	v_mov_b32_e32 v4, s50
	v_mov_b32_e32 v5, s51
	v_mov_b32_e32 v1, s4
	s_add_i32 s4, 0, 0x23950
	ds_write_b128 v1, v[2:5]
	v_mov_b32_e32 v2, s52
	v_mov_b32_e32 v3, s53
	v_mov_b32_e32 v4, s54
	v_mov_b32_e32 v5, s55
	v_mov_b32_e32 v1, s4
	s_add_i32 s4, 0, 0x23960
	ds_write_b128 v1, v[2:5]
	v_mov_b32_e32 v1, s4
	s_load_dwordx16 s[4:19], s[0:1], 0x80
	v_mov_b32_e32 v2, s56
	v_mov_b32_e32 v3, s57
	v_mov_b32_e32 v4, s58
	v_mov_b32_e32 v5, s59
	ds_write_b128 v1, v[2:5]
	v_mov_b32_e32 v2, s60
	v_mov_b32_e32 v3, s61
	v_mov_b32_e32 v4, s62
	v_mov_b32_e32 v5, s63
	v_mov_b32_e32 v1, s20
	ds_write_b128 v1, v[2:5]
	s_waitcnt lgkmcnt(0)
	v_mov_b32_e32 v2, s4
	s_add_i32 s4, 0, 0x23980
	v_mov_b32_e32 v3, s5
	v_mov_b32_e32 v4, s6
	v_mov_b32_e32 v5, s7
	v_mov_b32_e32 v1, s4
	s_add_i32 s4, 0, 0x23990
	ds_write_b128 v1, v[2:5]
	v_mov_b32_e32 v2, s8
	v_mov_b32_e32 v3, s9
	v_mov_b32_e32 v4, s10
	v_mov_b32_e32 v5, s11
	v_mov_b32_e32 v1, s4
	s_add_i32 s4, 0, 0x239a0
	ds_write_b128 v1, v[2:5]
	v_mov_b32_e32 v1, s4
	s_load_dwordx2 s[4:5], s[0:1], 0xc0
	v_mov_b32_e32 v2, s12
	v_mov_b32_e32 v3, s13
	v_mov_b32_e32 v4, s14
	v_mov_b32_e32 v5, s15
	s_add_i32 s6, 0, 0x239b0
	ds_write_b128 v1, v[2:5]
	v_mov_b32_e32 v2, s16
	v_mov_b32_e32 v3, s17
	v_mov_b32_e32 v4, s18
	v_mov_b32_e32 v5, s19
	v_mov_b32_e32 v1, s6
	s_add_i32 s6, 0, 0x239c0
	ds_write_b128 v1, v[2:5]
	v_mov_b32_e32 v1, s6
	s_waitcnt lgkmcnt(0)
	v_mov_b64_e32 v[2:3], s[4:5]
	ds_write_b64 v1, v[2:3]

; __device__ __forceinline__ int tidx() { int t = threadIdx.x; asm volatile("" : "+v"(t)); return t; }
; #define LAS __attribute__((address_space(3)))
; __device__ __forceinline__ void phase_prologue(const P& p, unsigned char* ws, LAS unsigned char* lds, int wg, int nwg) {
;     const int tid = tidx(), lane = tid & 63, wave = tid >> 6;
;     LAS float* scr = (LAS float*)(lds + wave * 16384);
;     const int gw = wg * NWAVES + wave, NGW = nwg * NWAVES;
;     constexpr int I_IN = (D / 64) * (NZ / 32), I_UH = (HW / 64) * (D / 32), I_UG = I_UH, I_OUT = (D / 64) * (D / 32), I_F1 = (D / 64) * (DFF / 32), I_F2 = (DFF / 64) * (D / 32), I_PL = (PLE / 64) * (D / 32), I_PG = I_OUT;
;     constexpr int I_LAYER = I_IN + I_UH + I_UG + I_OUT + I_F1 + I_F2 + I_PL + I_PG;
;     for (int it = gw; it < DEPTH * I_LAYER; it += NGW) {
;         const int l = it / I_LAYER; int r = it % I_LAYER;
.Lcv_entry:
	v_readlane_b32 s18, v249, 4
	s_mov_b32 s26, s2
	s_mov_b32 s24, s95
	v_readlane_b32 s19, v249, 5
	v_readlane_b32 s0, v250, 0
	s_cmp_eq_u32 s0, 1
	s_cbranch_scc0 .Lcv_m0
	v_readlane_b32 s26, v250, 4
	s_movk_i32 s24, 0x80
.Lcv_m0:
	s_add_i32 s0, 0, 0x23900
	v_mov_b32_e32 v1, s0
	ds_read_b128 v[2:5], v1
	s_add_i32 s0, 0, 0x23910
	v_mov_b32_e32 v1, s0
	s_add_i32 s0, 0, 0x23930
	ds_read_b128 v[6:9], v1
	v_mov_b32_e32 v1, s0
	s_waitcnt lgkmcnt(1)
	v_readfirstlane_b32 s17, v3
	v_readfirstlane_b32 s16, v2
	ds_read_b64 v[2:3], v1
	s_add_i32 s0, 0, 0x23940
	v_mov_b32_e32 v1, s0
	s_add_i32 s4, 0, 0x23950
	s_waitcnt lgkmcnt(1)
	v_readfirstlane_b32 s21, v7
	v_readfirstlane_b32 s20, v6
	ds_read_b64 v[6:7], v1
	v_mov_b32_e32 v1, s4
	v_readfirstlane_b32 s13, v5
	v_readfirstlane_b32 s12, v4
	s_waitcnt lgkmcnt(1)
	v_readfirstlane_b32 s1, v3
	v_readfirstlane_b32 s0, v2
	ds_read_b128 v[2:5], v1
	s_add_i32 s7, 0, 0x23968
	v_mov_b32_e32 v1, s7
	s_add_i32 s7, 0, 0x23988
	v_readfirstlane_b32 s3, v9
	v_readfirstlane_b32 s6, v8
	s_waitcnt lgkmcnt(1)
	v_readfirstlane_b32 s5, v7
	v_readfirstlane_b32 s4, v6
	ds_read2_b64 v[6:9], v1 offset1:1
	v_mov_b32_e32 v1, s7
	s_waitcnt lgkmcnt(1)
	v_readfirstlane_b32 s31, v3
	v_readfirstlane_b32 s30, v2
	v_readfirstlane_b32 s29, v5
	v_readfirstlane_b32 s28, v4
	ds_read2_b64 v[2:5], v1 offset1:1
	s_add_i32 s7, 0, 0x23998
	v_mov_b32_e32 v1, s7
	s_add_i32 s7, 0, 0x239a8
	s_waitcnt lgkmcnt(1)
	v_readfirstlane_b32 s35, v7
	v_readfirstlane_b32 s34, v6
	v_readfirstlane_b32 s37, v9
	v_readfirstlane_b32 s36, v8
	ds_read2_b64 v[6:9], v1 offset1:1
	v_mov_b32_e32 v1, s7
	s_waitcnt lgkmcnt(1)
	v_readfirstlane_b32 s39, v3
	v_readfirstlane_b32 s38, v2
	v_readfirstlane_b32 s41, v5
	v_readfirstlane_b32 s40, v4
	ds_read2_b64 v[2:5], v1 offset1:1
	s_waitcnt lgkmcnt(1)
	v_readfirstlane_b32 s42, v6
	v_mov_b32_e32 v1, v0
	v_mov_b32_e32 v6, v0
	s_waitcnt lgkmcnt(0)
	v_readfirstlane_b32 s48, v2
	s_lshl_b32 s22, s26, 3
	v_readfirstlane_b32 s49, v3
	v_ashrrev_i32_e32 v2, 6, v6
	v_and_b32_e32 v1, 63, v6
	v_add_u32_e32 v3, s22, v2
	v_readlane_b32 s7, v250, 1
	s_nop 1
	v_add_u32_e32 v254, s7, v3
	v_readlane_b32 s7, v250, 2
	v_readfirstlane_b32 s43, v7
	v_readfirstlane_b32 s47, v9
	v_readfirstlane_b32 s46, v8
	v_readfirstlane_b32 s53, v5
	v_readfirstlane_b32 s52, v4
	s_lshl_b32 s14, s24, 3
	v_cmp_gt_i32_e32 vcc, s7, v254
	v_lshlrev_b32_e32 v4, 3, v1
	s_and_saveexec_b64 s[54:55], vcc
	s_cbranch_execz .LBB0_49
	s_add_u32 s56, s18, 0x1ff14000
	s_addc_u32 s57, s19, 0
	s_add_u32 s58, s18, 0x1fb14000
	s_addc_u32 s59, s19, 0
	s_add_u32 s60, s18, 0x17b14000
	s_addc_u32 s61, s19, 0
	s_add_u32 s62, s18, 0xfb14000
	s_addc_u32 s63, s19, 0
	s_add_u32 s64, s18, 0xdb14000
	s_addc_u32 s65, s19, 0
	s_add_u32 s66, s18, 0xcb14000
	s_addc_u32 s67, s19, 0
	s_add_u32 s68, s18, 0xbb14000
	s_addc_u32 s69, s19, 0
	s_add_u32 s70, s18, 0x314000
	s_addc_u32 s71, s19, 0
	v_lshrrev_b32_e32 v8, 5, v1
	s_cmp_lg_u64 s[4:5], 0
	v_lshlrev_b32_e32 v12, 14, v2
	v_and_b32_e32 v10, 31, v6
	v_mul_u32_u24_e32 v17, 0x84, v8
	v_lshrrev_b32_e32 v7, 3, v1
	v_and_b32_e32 v14, 56, v4
	s_cselect_b64 s[74:75], -1, 0
	s_cmp_lg_u64 s[0:1], 0
	v_add_u32_e32 v9, 0, v12
	v_mov_b32_e32 v13, 0
	v_lshlrev_b32_e32 v16, 2, v10
	v_mul_u32_u24_e32 v11, 0x84, v14
	v_lshlrev_b32_e32 v15, 2, v7
	v_or_b32_e32 v12, v12, v17
	s_mov_b64 s[72:73], 0
	s_cselect_b64 s[76:77], -1, 0
	v_add3_u32 v5, v9, v16, v17
	v_add3_u32 v11, v9, v11, v15
	v_or_b32_e32 v15, 8, v7
	v_or_b32_e32 v56, 16, v7
	v_or_b32_e32 v57, 24, v7
	v_or_b32_e32 v58, 0xffffe400, v10
	v_mov_b32_e32 v9, v13
	v_add3_u32 v59, v12, v16, 0
	v_or_b32_e32 v60, 14, v8
	v_or_b32_e32 v61, 12, v8
	v_or_b32_e32 v62, 10, v8
	v_or_b32_e32 v63, 8, v8
	v_or_b32_e32 v64, 6, v8
	v_or_b32_e32 v65, 4, v8
	v_or_b32_e32 v66, 2, v8
	s_movk_i32 s7, 0xe0
	s_mov_b32 s15, 0xb040
	s_movk_i32 s23, 0x80
	s_movk_i32 s25, 0x7000
	s_mov_b64 s[78:79], 0x7000
	v_readlane_b32 s27, v250, 3
	v_mov_b32_e32 v67, 0x3db504f3
	v_mov_b32_e32 v68, v254
	s_branch .LBB0_12

; __device__ __forceinline__ void phase_prologue(const P& p, unsigned char* ws, LAS unsigned char* lds, int wg, int nwg) {
;     ...
;     }
;     float* lbs = (float*)(ws + WS_LBS);
;     for (int c = wg * NTHR + tid; c < HW; c += nwg * NTHR) {
;         float e[DEPTH], mx = -1e30f, sum = 0.f;
; #pragma unroll
;         for (int i = 0; i < DEPTH; ++i) { e[i] = p.lbp[i * HW + c]; mx = fmaxf(mx, e[i]); }
.LBB0_49:
	s_or_b64 exec, exec, s[54:55]
	v_readlane_b32 s0, v250, 0
	s_cmp_eq_u32 s0, 1
	s_cbranch_scc1 .Lcv_rett
	s_cmp_eq_u32 s0, 2
	s_cbranch_scc1 .Lcv_p0c
	s_mov_b32 s0, 0x21300
	v_writelane_b32 v250, s0, 1
	s_mov_b32 s0, 0x21c00
	v_writelane_b32 v250, s0, 2
	s_mov_b32 s0, 0x21bff
	v_writelane_b32 v250, s0, 3
	s_mov_b32 s0, 2
	v_writelane_b32 v250, s0, 0
	s_branch .Lcv_entry
.Lcv_rett:
	s_branch .Lcv_return
.Lcv_p0c:
	v_lshl_add_u32 v8, s26, 9, v6
	s_movk_i32 s0, 0x400
	v_cmp_gt_i32_e32 vcc, s0, v8
	s_and_saveexec_b64 s[30:31], vcc
	s_cbranch_execz .LBB0_52
	s_lshl_b32 s34, s24, 9
	v_ashrrev_i32_e32 v9, 31, v8
	s_ashr_i32 s35, s34, 31
	v_lshlrev_b64 v[10:11], 2, v[8:9]
	s_lshl_b64 s[36:37], s[34:35], 2
	s_mov_b64 s[38:39], 0
	s_mov_b32 s7, 0xf149f2ca
	v_mov_b32_e32 v5, 0
	s_mov_b32 s15, 0x103000
	s_movk_i32 s23, 0x3ff
	s_mov_b64 s[40:41], s[18:19]

; #define LAS __attribute__((address_space(3)))
; __device__ __forceinline__ void phase_prologue(const P& p, unsigned char* ws, LAS unsigned char* lds, int wg, int nwg) {
;     ...
;     for (int it = gw; it < DEPTH * I_LAYER; it += NGW) {
; __device__ __forceinline__ void phase_rec(const P& p, unsigned char* ws, int l, LAS unsigned char* lds, int wg, int nwg) {
;     int lrank = wg, nloop = nwg, srank = wg, nstr = nwg;
;     const bool split = nwg >= 16;
;     if (split) { const int grp = wg >> 3, ngrp = (nwg + 7) >> 3, nlg = (ngrp + 1) >> 1;
;         const int full_l = nlg * 8 - ((ngrp & 1) ? (ngrp * 8 - nwg) : 0), full_s = nwg - full_l;
;         nloop = full_l; nstr = full_s; lrank = (grp >> 1) * 8 + (wg & 7); srank = (grp >> 1) * 8 + (wg & 7);
;         if (grp & 1) lrank = 1 << 30; else srank = 1 << 30; }
;     for (int rl = 0; rl < REP_LOOP; ++rl) for (int tk = lrank; tk < 128; tk += nloop) rec_loop_task(p, ws, l, lds, tk);
;     const int nlk = split ? LK_ITEMS * nloop : 0;
;     for (int rs = 0; rs < REP_SST; ++rs) {
;     if (split) for (int it = lrank; it < nlk; it += nloop) rec_sample_item<HV, false>(p, ws, l, lds, it >> 3, it & 7);
;     for (int it = nlk + srank; it < DECB * HH; it += nstr) rec_sample_item<HV, false>(p, ws, l, lds, it >> 3, it & 7);
;     for (int it = srank; it < DECB * GH; it += nstr) rec_sample_item<GV, true>(p, ws, l, lds, it >> 2, it & 3); }
; }
.LBB0_1145:
	v_readlane_b32 s0, v248, 27
	s_cmp_gt_u32 s0, 2
	s_cbranch_scc1 .Lcv_skip
	v_readlane_b32 s1, v248, 19
	s_bitcmp1_b32 s1, 3
	s_cbranch_scc0 .Lcv_skip
	s_waitcnt lgkmcnt(0)
	s_barrier
	v_writelane_b32 v251, s3, 0
	v_writelane_b32 v251, s4, 1
	v_writelane_b32 v251, s5, 2
	v_writelane_b32 v251, s6, 3
	v_writelane_b32 v251, s7, 4
	v_writelane_b32 v251, s8, 5
	v_writelane_b32 v251, s9, 6
	v_writelane_b32 v251, s10, 7
	v_writelane_b32 v251, s11, 8
	v_writelane_b32 v251, s12, 9
	v_writelane_b32 v251, s13, 10
	v_writelane_b32 v251, s14, 11
	v_writelane_b32 v251, s15, 12
	v_writelane_b32 v251, s16, 13
	v_writelane_b32 v251, s17, 14
	v_writelane_b32 v251, s18, 15
	v_writelane_b32 v251, s19, 16
	v_writelane_b32 v251, s20, 17
	v_writelane_b32 v251, s21, 18
	v_writelane_b32 v251, s23, 20
	v_writelane_b32 v251, s24, 21
	v_writelane_b32 v251, s25, 22
	v_writelane_b32 v251, s26, 23
	v_writelane_b32 v251, s27, 24
	v_writelane_b32 v251, s28, 25
	v_writelane_b32 v251, s29, 26
	v_writelane_b32 v251, s30, 27
	v_writelane_b32 v251, s31, 28
	v_writelane_b32 v251, s32, 29
	v_writelane_b32 v251, s33, 30
	v_writelane_b32 v251, s34, 31
	v_writelane_b32 v251, s35, 32
	v_writelane_b32 v251, s36, 33
	v_writelane_b32 v251, s37, 34
	v_writelane_b32 v251, s38, 35
	v_writelane_b32 v251, s39, 36
	v_writelane_b32 v251, s40, 37
	v_writelane_b32 v251, s41, 38
	v_writelane_b32 v251, s42, 39
	v_writelane_b32 v251, s43, 40
	v_writelane_b32 v251, s44, 41
	v_writelane_b32 v251, s45, 42
	v_writelane_b32 v251, s46, 43
	v_writelane_b32 v251, s47, 44
	v_writelane_b32 v251, s48, 45
	v_writelane_b32 v251, s49, 46
	v_writelane_b32 v251, s50, 47
	v_writelane_b32 v251, s51, 48
	v_writelane_b32 v251, s52, 49
	v_writelane_b32 v251, s53, 50
	v_writelane_b32 v251, s54, 51
	v_writelane_b32 v251, s55, 52
	v_writelane_b32 v251, s56, 53
	v_writelane_b32 v251, s57, 54
	v_writelane_b32 v251, s58, 55
	v_writelane_b32 v251, s59, 56
	v_writelane_b32 v251, s60, 57
	v_writelane_b32 v251, s61, 58
	v_writelane_b32 v251, s62, 59
	v_writelane_b32 v251, s63, 60
	v_writelane_b32 v251, s64, 61
	v_writelane_b32 v251, s65, 62
	v_writelane_b32 v251, s66, 63
	v_writelane_b32 v252, s67, 0
	v_writelane_b32 v252, s68, 1
	v_writelane_b32 v252, s69, 2
	v_writelane_b32 v252, s70, 3
	v_writelane_b32 v252, s71, 4
	v_writelane_b32 v252, s72, 5
	v_writelane_b32 v252, s73, 6
	v_writelane_b32 v252, s74, 7
	v_writelane_b32 v252, s75, 8
	v_writelane_b32 v252, s76, 9
	v_writelane_b32 v252, s77, 10
	v_writelane_b32 v252, s78, 11
	v_writelane_b32 v252, s79, 12
	v_writelane_b32 v252, s80, 13
	v_writelane_b32 v252, s81, 14
	v_writelane_b32 v252, s82, 15
	v_writelane_b32 v252, s83, 16
	v_writelane_b32 v252, s84, 17
	v_writelane_b32 v252, s85, 18
	v_writelane_b32 v252, s86, 19
	v_writelane_b32 v252, s87, 20
	v_writelane_b32 v252, s88, 21
	v_writelane_b32 v252, s89, 22
	v_writelane_b32 v252, s90, 23
	v_writelane_b32 v252, s91, 24
	v_writelane_b32 v252, s92, 25
	v_writelane_b32 v252, s93, 26
	v_writelane_b32 v252, s94, 27
	v_writelane_b32 v252, s95, 28
	v_writelane_b32 v252, s96, 29
	v_writelane_b32 v252, s97, 30
	v_writelane_b32 v252, s98, 31
	v_writelane_b32 v252, s99, 32
	v_mov_b32_e32 v253, v1
	s_lshr_b32 s22, s1, 4
	s_lshl_b32 s22, s22, 3
	s_and_b32 s1, s1, 7
	s_or_b32 s1, s22, s1
	v_writelane_b32 v250, s1, 4
	s_mul_i32 s22, s0, 0x2000
	s_add_i32 s22, s22, 0x1b300
	v_writelane_b32 v250, s22, 1
	s_add_i32 s22, s22, 0x2000
	v_writelane_b32 v250, s22, 2
	s_add_i32 s22, s22, -1
	v_writelane_b32 v250, s22, 3
	s_mov_b32 s22, 1
	v_writelane_b32 v250, s22, 0
	s_branch .Lcv_entry
.Lcv_return:
	v_readlane_b32 s3, v251, 0
	v_readlane_b32 s4, v251, 1
	v_readlane_b32 s5, v251, 2
	v_readlane_b32 s6, v251, 3
	v_readlane_b32 s7, v251, 4
	v_readlane_b32 s8, v251, 5
	v_readlane_b32 s9, v251, 6
	v_readlane_b32 s10, v251, 7
	v_readlane_b32 s11, v251, 8
	v_readlane_b32 s12, v251, 9
	v_readlane_b32 s13, v251, 10
	v_readlane_b32 s14, v251, 11
	v_readlane_b32 s15, v251, 12
	v_readlane_b32 s16, v251, 13
	v_readlane_b32 s17, v251, 14
	v_readlane_b32 s18, v251, 15
	v_readlane_b32 s19, v251, 16
	v_readlane_b32 s20, v251, 17
	v_readlane_b32 s21, v251, 18
	v_readlane_b32 s23, v251, 20
	v_readlane_b32 s24, v251, 21
	v_readlane_b32 s25, v251, 22
	v_readlane_b32 s26, v251, 23
	v_readlane_b32 s27, v251, 24
	v_readlane_b32 s28, v251, 25
	v_readlane_b32 s29, v251, 26
	v_readlane_b32 s30, v251, 27
	v_readlane_b32 s31, v251, 28
	v_readlane_b32 s32, v251, 29
	v_readlane_b32 s33, v251, 30
	v_readlane_b32 s34, v251, 31
	v_readlane_b32 s35, v251, 32
	v_readlane_b32 s36, v251, 33
	v_readlane_b32 s37, v251, 34
	v_readlane_b32 s38, v251, 35
	v_readlane_b32 s39, v251, 36
	v_readlane_b32 s40, v251, 37
	v_readlane_b32 s41, v251, 38
	v_readlane_b32 s42, v251, 39
	v_readlane_b32 s43, v251, 40
	v_readlane_b32 s44, v251, 41
	v_readlane_b32 s45, v251, 42
	v_readlane_b32 s46, v251, 43
	v_readlane_b32 s47, v251, 44
	v_readlane_b32 s48, v251, 45
	v_readlane_b32 s49, v251, 46
	v_readlane_b32 s50, v251, 47
	v_readlane_b32 s51, v251, 48
	v_readlane_b32 s52, v251, 49
	v_readlane_b32 s53, v251, 50
	v_readlane_b32 s54, v251, 51
	v_readlane_b32 s55, v251, 52
	v_readlane_b32 s56, v251, 53
	v_readlane_b32 s57, v251, 54
	v_readlane_b32 s58, v251, 55
	v_readlane_b32 s59, v251, 56
	v_readlane_b32 s60, v251, 57
	v_readlane_b32 s61, v251, 58
	v_readlane_b32 s62, v251, 59
	v_readlane_b32 s63, v251, 60
	v_readlane_b32 s64, v251, 61
	v_readlane_b32 s65, v251, 62
	v_readlane_b32 s66, v251, 63
	v_readlane_b32 s67, v252, 0
	v_readlane_b32 s68, v252, 1
	v_readlane_b32 s69, v252, 2
	v_readlane_b32 s70, v252, 3
	v_readlane_b32 s71, v252, 4
	v_readlane_b32 s72, v252, 5
	v_readlane_b32 s73, v252, 6
	v_readlane_b32 s74, v252, 7
	v_readlane_b32 s75, v252, 8
	v_readlane_b32 s76, v252, 9
	v_readlane_b32 s77, v252, 10
	v_readlane_b32 s78, v252, 11
	v_readlane_b32 s79, v252, 12
	v_readlane_b32 s80, v252, 13
	v_readlane_b32 s81, v252, 14
	v_readlane_b32 s82, v252, 15
	v_readlane_b32 s83, v252, 16
	v_readlane_b32 s84, v252, 17
	v_readlane_b32 s85, v252, 18
	v_readlane_b32 s86, v252, 19
	v_readlane_b32 s87, v252, 20
	v_readlane_b32 s88, v252, 21
	v_readlane_b32 s89, v252, 22
	v_readlane_b32 s90, v252, 23
	v_readlane_b32 s91, v252, 24
	v_readlane_b32 s92, v252, 25
	v_readlane_b32 s93, v252, 26
	v_readlane_b32 s94, v252, 27
	v_readlane_b32 s95, v252, 28
	v_readlane_b32 s96, v252, 29
	v_readlane_b32 s97, v252, 30
	v_readlane_b32 s98, v252, 31
	v_readlane_b32 s99, v252, 32
	v_mov_b32_e32 v1, v253
	s_mov_b32 s22, 0
	v_writelane_b32 v250, s22, 0
